# Out GEMM: half of the 5-tile workgroups start the phase ~25us late so their memory-bound residual epilogues overlap the other half's K-loops
# baseline (speedup 1.0000x reference)
; __global__ void __launch_bounds__(NTHR, 2) mega_fwd(KArgs a) {
;     ...
;         {
;             pg8::Gemm g{(const bf16_t*)(ws + WS_O), (const bf16_t*)(wl + W_OUT), MROWS, 1024, 1024}; pg8::StaticOrder S; S.init(MROWS, 1024, G, bx);
;             pg8::EpiResid E{LEAD, OUT, 1.0f, XN, a.in[17] + (size_t)l * DM, SSb + (size_t)((cons + 1) & 1) * MROWS, nullptr, nullptr};
;             pg8::gemm_phase<pg8::EpiResid, pg8::StaticOrder, true, true>(lds, g, S, E);
.LBB0_1064:
	s_or_b64 exec, exec, s[0:1]
	s_cmp_lt_u32 s2, 24
	s_cbranch_scc1 .Lstg_out_done
	s_bitcmp1_b32 s2, 3
	s_cbranch_scc0 .Lstg_out_done
	s_movk_i32 s4, 7
.Lstg_out_loop:
	s_sleep 127
	s_add_i32 s4, s4, -1
	s_cmp_lg_u32 s4, 0
	s_cbranch_scc1 .Lstg_out_loop
.Lstg_out_done:
	v_readlane_b32 s4, v253, 46
	v_readlane_b32 s5, v253, 47
	v_mov_b32_e32 v0, v252
	s_waitcnt lgkmcnt(0)
	v_cndmask_b32_e64 v2, 0, 1, s[4:5]
	s_barrier
	v_cmp_ne_u32_e64 s[0:1], 1, v2
	s_andn2_b64 vcc, exec, s[4:5]
	v_readfirstlane_b32 s14, v0
	s_cbranch_vccnz .LBB0_1066
	v_readlane_b32 s4, v253, 62
	s_mov_b32 s26, s4
	v_readlane_b32 s4, v253, 63
